# speedup vs baseline: 1.0180x; 1.0180x over previous
; template <int EPI, int AMAP, int KOFFMODE, int K>
; __device__ __forceinline__ void gemm_phase(unsigned char* smem, const bf16_t* A, int lda, const bf16_t* Bt, int NT, const EpiArgs& ea) {
;     ...
;         for (int kt = 0; kt < nk; ++kt) {
;             if (kt + 1 < nk) GEMM_DMA(m0, n0, kt + 1, cur ^ 1);
;             else if (have_next) GEMM_DMA(m0n, n0n, 0, cur ^ 1);
;             const unsigned char* Ac = smem + cur * STGB + (wm * 128 + l31) * 128;
;             const unsigned char* Bc = smem + cur * STGB + 32768 + (wn * 64 + l31) * 128;
;             bf16x8 fa[2][4], fb[2][2];
;             fb[0][0] = *(const bf16x8*)(Bc + (((0) ^ yz) & 7) * 16);
;             fb[0][1] = *(const bf16x8*)(Bc + 32 * 128 + (((0) ^ yz) & 7) * 16);
; #pragma unroll
;             for (int i = 0; i < 4; ++i) fa[0][i] = *(const bf16x8*)(Ac + i * 32 * 128 + (((0) ^ yz) & 7) * 16);
; #pragma unroll
;             for (int s = 0; s < 4; ++s) {
;                 if (s < 3) {
;                     const int o_ = (((2 * (s + 1)) ^ yz) & 7) * 16;
;                     fb[(s + 1) & 1][0] = *(const bf16x8*)(Bc + o_);
;                     fb[(s + 1) & 1][1] = *(const bf16x8*)(Bc + 32 * 128 + o_);
; #pragma unroll
;                     for (int i = 0; i < 4; ++i) fa[(s + 1) & 1][i] = *(const bf16x8*)(Ac + i * 32 * 128 + o_);
;                 }
; #pragma unroll
;                 for (int i = 0; i < 4; ++i) {
;                     acc[i][0] = __builtin_amdgcn_mfma_f32_32x32x16_bf16(fa[s & 1][i], fb[s & 1][0], acc[i][0], 0, 0, 0);
;                     acc[i][1] = __builtin_amdgcn_mfma_f32_32x32x16_bf16(fa[s & 1][i], fb[s & 1][1], acc[i][1], 0, 0, 0);
;                 }
;                 __builtin_amdgcn_sched_barrier(0);
;             }
;             if (kt + 1 < nk) asm volatile("s_waitcnt vmcnt(0)" ::: "memory");
;             __builtin_amdgcn_s_barrier();
.LBB0_461:
	s_mov_b32 s9, s13
	s_lshl_b32 s13, s9, 16
	s_xor_b32 s12, s13, 0x10000
	v_readfirstlane_b32 vcc_lo, v143
	s_nop 0
	s_add_u32 vcc_lo, vcc_lo, s12
	s_add_u32 s14, s4, 0xb240080
	s_addc_u32 s15, s5, 0
	s_mov_b32 m0, vcc_lo
	v_lshl_add_u64 v[164:165], v[136:137], 0, s[14:15]
	global_load_lds_dwordx4 v[164:165], off
	s_add_u32 s14, s4, 0xb270080
	s_addc_u32 s15, s5, 0
	s_add_u32 m0, vcc_lo, 0x2000
	v_lshl_add_u64 v[164:165], v[136:137], 0, s[14:15]
	global_load_lds_dwordx4 v[164:165], off
	s_add_u32 s14, s4, 0xb2a0080
	s_addc_u32 s15, s5, 0
	s_add_u32 m0, vcc_lo, 0x4000
	v_lshl_add_u64 v[164:165], v[136:137], 0, s[14:15]
	global_load_lds_dwordx4 v[164:165], off
	s_add_u32 s14, s4, 0xb2d0080
	s_addc_u32 s15, s5, 0
	s_add_u32 m0, vcc_lo, 0x6000
	v_lshl_add_u64 v[164:165], v[136:137], 0, s[14:15]
	global_load_lds_dwordx4 v[164:165], off
	s_add_u32 s14, s4, 0xb00080
	s_addc_u32 s15, s5, 0
	s_add_u32 m0, vcc_lo, 0x8000
	v_lshl_add_u64 v[164:165], v[138:139], 0, s[14:15]
	global_load_lds_dwordx4 v[164:165], off
	s_add_u32 s14, s4, 0xb30080
	s_addc_u32 s15, s5, 0
	s_add_u32 m0, vcc_lo, 0xa000
	v_lshl_add_u64 v[164:165], v[138:139], 0, s[14:15]
	global_load_lds_dwordx4 v[164:165], off
	s_add_u32 s14, s4, 0xb60080
	s_addc_u32 s15, s5, 0
	s_add_u32 m0, vcc_lo, 0xc000
	v_lshl_add_u64 v[164:165], v[138:139], 0, s[14:15]
	global_load_lds_dwordx4 v[164:165], off
	s_add_u32 s14, s4, 0xb90080
	s_addc_u32 s15, s5, 0
	s_add_u32 m0, vcc_lo, 0xe000
	v_lshl_add_u64 v[164:165], v[138:139], 0, s[14:15]
	global_load_lds_dwordx4 v[164:165], off
	v_add3_u32 v155, s13, v150, v149
	v_add_u32_e32 v155, v155, v152
	v_add3_u32 v0, s13, v147, v149
	v_add_u32_e32 v0, v0, v152
	ds_read_b128 v[208:211], v155 offset:32768
	ds_read_b128 v[212:215], v155 offset:36864
	s_waitcnt lgkmcnt(5)
	v_mfma_f32_32x32x16_bf16 v[114:129], v[192:195], v[156:159], v[114:129]
	v_mfma_f32_32x32x16_bf16 v[98:113], v[192:195], v[160:163], v[98:113]
	ds_read_b128 v[192:195], v0
	s_waitcnt lgkmcnt(5)
	v_mfma_f32_32x32x16_bf16 v[82:97], v[196:199], v[156:159], v[82:97]
	v_mfma_f32_32x32x16_bf16 v[66:81], v[196:199], v[160:163], v[66:81]
	ds_read_b128 v[196:199], v0 offset:4096
	s_waitcnt lgkmcnt(5)
	v_mfma_f32_32x32x16_bf16 v[50:65], v[200:203], v[156:159], v[50:65]
	v_mfma_f32_32x32x16_bf16 v[34:49], v[200:203], v[160:163], v[34:49]
	ds_read_b128 v[200:203], v0 offset:8192
	s_waitcnt lgkmcnt(5)
	v_mfma_f32_32x32x16_bf16 v[18:33], v[204:207], v[156:159], v[18:33]
	v_mfma_f32_32x32x16_bf16 v[2:17], v[204:207], v[160:163], v[2:17]
	ds_read_b128 v[204:207], v0 offset:12288
	v_add3_u32 v155, s13, v150, v149
	v_add_u32_e32 v155, v155, v153
	v_add3_u32 v0, s13, v147, v149
	v_add_u32_e32 v0, v0, v153
	ds_read_b128 v[156:159], v155 offset:32768
	ds_read_b128 v[160:163], v155 offset:36864
	s_waitcnt lgkmcnt(5)
	v_mfma_f32_32x32x16_bf16 v[114:129], v[192:195], v[208:211], v[114:129]
	v_mfma_f32_32x32x16_bf16 v[98:113], v[192:195], v[212:215], v[98:113]
	ds_read_b128 v[192:195], v0
	s_waitcnt lgkmcnt(5)
	v_mfma_f32_32x32x16_bf16 v[82:97], v[196:199], v[208:211], v[82:97]
	v_mfma_f32_32x32x16_bf16 v[66:81], v[196:199], v[212:215], v[66:81]
	ds_read_b128 v[196:199], v0 offset:4096
	s_waitcnt lgkmcnt(5)
	v_mfma_f32_32x32x16_bf16 v[50:65], v[200:203], v[208:211], v[50:65]
	v_mfma_f32_32x32x16_bf16 v[34:49], v[200:203], v[212:215], v[34:49]
	ds_read_b128 v[200:203], v0 offset:8192
	s_waitcnt lgkmcnt(5)
	v_mfma_f32_32x32x16_bf16 v[18:33], v[204:207], v[208:211], v[18:33]
	v_mfma_f32_32x32x16_bf16 v[2:17], v[204:207], v[212:215], v[2:17]
	ds_read_b128 v[204:207], v0 offset:12288
	v_add3_u32 v155, s13, v150, v149
	v_add_u32_e32 v155, v155, v154
	v_add3_u32 v0, s13, v147, v149
	v_add_u32_e32 v0, v0, v154
	ds_read_b128 v[208:211], v155 offset:32768
	ds_read_b128 v[212:215], v155 offset:36864
	s_waitcnt lgkmcnt(5)
	v_mfma_f32_32x32x16_bf16 v[114:129], v[192:195], v[156:159], v[114:129]
	v_mfma_f32_32x32x16_bf16 v[98:113], v[192:195], v[160:163], v[98:113]
	ds_read_b128 v[192:195], v0
	s_waitcnt lgkmcnt(5)
	v_mfma_f32_32x32x16_bf16 v[82:97], v[196:199], v[156:159], v[82:97]
	v_mfma_f32_32x32x16_bf16 v[66:81], v[196:199], v[160:163], v[66:81]
	ds_read_b128 v[196:199], v0 offset:4096
	s_waitcnt lgkmcnt(5)
	v_mfma_f32_32x32x16_bf16 v[50:65], v[200:203], v[156:159], v[50:65]
	v_mfma_f32_32x32x16_bf16 v[34:49], v[200:203], v[160:163], v[34:49]
	ds_read_b128 v[200:203], v0 offset:8192
	s_waitcnt lgkmcnt(5)
	v_mfma_f32_32x32x16_bf16 v[18:33], v[204:207], v[156:159], v[18:33]
	v_mfma_f32_32x32x16_bf16 v[2:17], v[204:207], v[160:163], v[2:17]
	ds_read_b128 v[204:207], v0 offset:12288
	s_waitcnt lgkmcnt(3)
	v_mfma_f32_32x32x16_bf16 v[114:129], v[192:195], v[208:211], v[114:129]
	v_mfma_f32_32x32x16_bf16 v[98:113], v[192:195], v[212:215], v[98:113]
	s_waitcnt lgkmcnt(2)
	v_mfma_f32_32x32x16_bf16 v[82:97], v[196:199], v[208:211], v[82:97]
	v_mfma_f32_32x32x16_bf16 v[66:81], v[196:199], v[212:215], v[66:81]
	s_waitcnt lgkmcnt(0)
	s_waitcnt vmcnt(0)
	s_barrier
; template <int EPI, int AMAP, int KOFFMODE, int K>
; __device__ __forceinline__ void gemm_phase(unsigned char* smem, const bf16_t* A, int lda, const bf16_t* Bt, int NT, const EpiArgs& ea) {
;     ...
;         for (int kt = 0; kt < nk; ++kt) {
;             if (kt + 1 < nk) GEMM_DMA(m0, n0, kt + 1, cur ^ 1);
;             else if (have_next) GEMM_DMA(m0n, n0n, 0, cur ^ 1);
;             const unsigned char* Ac = smem + cur * STGB + (wm * 128 + l31) * 128;
;             const unsigned char* Bc = smem + cur * STGB + 32768 + (wn * 64 + l31) * 128;
;             bf16x8 fa[2][4], fb[2][2];
;             fb[0][0] = *(const bf16x8*)(Bc + (((0) ^ yz) & 7) * 16);
;             fb[0][1] = *(const bf16x8*)(Bc + 32 * 128 + (((0) ^ yz) & 7) * 16);
; #pragma unroll
;             for (int i = 0; i < 4; ++i) fa[0][i] = *(const bf16x8*)(Ac + i * 32 * 128 + (((0) ^ yz) & 7) * 16);
; #pragma unroll
;             for (int s = 0; s < 4; ++s) {
;                 if (s < 3) {
;                     const int o_ = (((2 * (s + 1)) ^ yz) & 7) * 16;
;                     fb[(s + 1) & 1][0] = *(const bf16x8*)(Bc + o_);
;                     fb[(s + 1) & 1][1] = *(const bf16x8*)(Bc + 32 * 128 + o_);
; #pragma unroll
;                     for (int i = 0; i < 4; ++i) fa[(s + 1) & 1][i] = *(const bf16x8*)(Ac + i * 32 * 128 + o_);
;                 }
; #pragma unroll
;                 for (int i = 0; i < 4; ++i) {
;                     acc[i][0] = __builtin_amdgcn_mfma_f32_32x32x16_bf16(fa[s & 1][i], fb[s & 1][0], acc[i][0], 0, 0, 0);
;                     acc[i][1] = __builtin_amdgcn_mfma_f32_32x32x16_bf16(fa[s & 1][i], fb[s & 1][1], acc[i][1], 0, 0, 0);
;                 }
;                 __builtin_amdgcn_sched_barrier(0);
;             }
;             if (kt + 1 < nk) asm volatile("s_waitcnt vmcnt(0)" ::: "memory");
;             __builtin_amdgcn_s_barrier();
;             cur ^= 1;
;         }
	v_add3_u32 v155, s12, v150, v149
	v_add_u32_e32 v155, v155, v151
	v_add3_u32 v0, s12, v147, v149
	v_add_u32_e32 v0, v0, v151
	ds_read_b128 v[156:159], v155 offset:32768
	ds_read_b128 v[160:163], v155 offset:36864
	ds_read_b128 v[192:195], v0
	ds_read_b128 v[196:199], v0 offset:4096
	v_mfma_f32_32x32x16_bf16 v[50:65], v[200:203], v[208:211], v[50:65]
	v_mfma_f32_32x32x16_bf16 v[34:49], v[200:203], v[212:215], v[34:49]
	ds_read_b128 v[200:203], v0 offset:8192
	v_mfma_f32_32x32x16_bf16 v[18:33], v[204:207], v[208:211], v[18:33]
	v_mfma_f32_32x32x16_bf16 v[2:17], v[204:207], v[212:215], v[2:17]
	ds_read_b128 v[204:207], v0 offset:12288
	s_xor_b32 s13, s9, 1
	s_add_u32 s4, s4, 0x80
	s_addc_u32 s5, s5, 0
	s_cmpk_eq_i32 s4, 0xb80
	s_cbranch_scc0 .LBB0_461
	s_waitcnt lgkmcnt(0)
	s_andn2_b64 vcc, exec, s[2:3]
	s_lshl_b32 s2, s13, 16
	s_cbranch_vccnz .LBB0_453
	v_add_u32_e32 v0, s8, v142
	s_xor_b32 s3, s2, 0x10000
	v_mad_i64_i32 v[138:139], s[4:5], v0, s37, v[130:131]
	v_add_u32_e32 v0, s3, v143
	v_add_u32_e32 v136, s7, v142
	v_add_u32_e32 v155, 0x8000, v0
	v_readfirstlane_b32 s3, v0
	v_mad_i64_i32 v[136:137], s[4:5], v136, s37, v[132:133]
	s_mov_b32 m0, s3
	v_readfirstlane_b32 s3, v155
	v_add_u32_e32 v155, 0x2000, v0
	global_load_lds_dwordx4 v[138:139], off
	s_mov_b32 m0, s3
	s_mov_b64 s[4:5], 0x30000
	v_readfirstlane_b32 s3, v155
	v_add_u32_e32 v155, 0xa000, v0
	global_load_lds_dwordx4 v[136:137], off
	v_lshl_add_u64 v[156:157], v[138:139], 0, s[4:5]
	s_mov_b32 m0, s3
	v_readfirstlane_b32 s3, v155
	v_add_u32_e32 v155, 0x4000, v0
	global_load_lds_dwordx4 v[156:157], off
	v_lshl_add_u64 v[156:157], v[136:137], 0, s[4:5]
	s_mov_b32 m0, s3
	s_mov_b64 s[4:5], 0x60000
	v_readfirstlane_b32 s3, v155
	v_add_u32_e32 v155, 0xc000, v0
	global_load_lds_dwordx4 v[156:157], off
	v_lshl_add_u64 v[156:157], v[138:139], 0, s[4:5]
	s_mov_b32 m0, s3
	v_readfirstlane_b32 s3, v155
	v_add_u32_e32 v155, 0x6000, v0
	global_load_lds_dwordx4 v[156:157], off
	v_lshl_add_u64 v[156:157], v[136:137], 0, s[4:5]
	s_mov_b32 m0, s3
	s_mov_b64 s[4:5], 0x90000
	v_readfirstlane_b32 s3, v155
	v_add_u32_e32 v0, 0xe000, v0
	global_load_lds_dwordx4 v[156:157], off
	v_lshl_add_u64 v[138:139], v[138:139], 0, s[4:5]
	s_mov_b32 m0, s3
	v_readfirstlane_b32 s3, v0
	global_load_lds_dwordx4 v[138:139], off
	v_lshl_add_u64 v[136:137], v[136:137], 0, s[4:5]
	s_mov_b32 m0, s3
	s_nop 0
	global_load_lds_dwordx4 v[136:137], off
	s_branch .LBB0_453

; template <int EPI, int AMAP, int KOFFMODE, int K>
; __device__ __forceinline__ void gemm_phase(unsigned char* smem, const bf16_t* A, int lda, const bf16_t* Bt, int NT, const EpiArgs& ea) {
;     ...
;         for (int kt = 0; kt < nk; ++kt) {
;             if (kt + 1 < nk) GEMM_DMA(m0, n0, kt + 1, cur ^ 1);
;             else if (have_next) GEMM_DMA(m0n, n0n, 0, cur ^ 1);
;             const unsigned char* Ac = smem + cur * STGB + (wm * 128 + l31) * 128;
;             const unsigned char* Bc = smem + cur * STGB + 32768 + (wn * 64 + l31) * 128;
;             bf16x8 fa[2][4], fb[2][2];
;             fb[0][0] = *(const bf16x8*)(Bc + (((0) ^ yz) & 7) * 16);
;             fb[0][1] = *(const bf16x8*)(Bc + 32 * 128 + (((0) ^ yz) & 7) * 16);
; #pragma unroll
;             for (int i = 0; i < 4; ++i) fa[0][i] = *(const bf16x8*)(Ac + i * 32 * 128 + (((0) ^ yz) & 7) * 16);
; #pragma unroll
;             for (int s = 0; s < 4; ++s) {
;                 if (s < 3) {
;                     const int o_ = (((2 * (s + 1)) ^ yz) & 7) * 16;
;                     fb[(s + 1) & 1][0] = *(const bf16x8*)(Bc + o_);
;                     fb[(s + 1) & 1][1] = *(const bf16x8*)(Bc + 32 * 128 + o_);
; #pragma unroll
;                     for (int i = 0; i < 4; ++i) fa[(s + 1) & 1][i] = *(const bf16x8*)(Ac + i * 32 * 128 + o_);
;                 }
; #pragma unroll
;                 for (int i = 0; i < 4; ++i) {
;                     acc[i][0] = __builtin_amdgcn_mfma_f32_32x32x16_bf16(fa[s & 1][i], fb[s & 1][0], acc[i][0], 0, 0, 0);
;                     acc[i][1] = __builtin_amdgcn_mfma_f32_32x32x16_bf16(fa[s & 1][i], fb[s & 1][1], acc[i][1], 0, 0, 0);
;                 }
;                 __builtin_amdgcn_sched_barrier(0);
;             }
;             if (kt + 1 < nk) asm volatile("s_waitcnt vmcnt(0)" ::: "memory");
;             __builtin_amdgcn_s_barrier();
.LBB0_927:
	s_lshr_b32 s14, s12, 1
	s_mulk_i32 s14, 0xc0
	s_and_b32 s20, s13, 64
	s_add_i32 s20, s14, s20
	s_mov_b32 s9, s15
	s_lshl_b32 s15, s9, 16
	s_xor_b32 s14, s15, 0x10000
	v_readfirstlane_b32 s28, v143
	s_nop 0
	s_add_u32 s28, s28, s14
	s_lshl_b64 s[34:35], s[20:21], 1
	s_mov_b32 m0, s28
	v_lshl_add_u64 v[164:165], v[136:137], 0, s[34:35]
	global_load_lds_dwordx4 v[164:165], off
	s_lshl_b64 s[34:35], s[20:21], 1
	s_add_u32 s34, s34, 0x60000
	s_addc_u32 s35, s35, 0
	s_add_u32 m0, s28, 0x2000
	v_lshl_add_u64 v[164:165], v[136:137], 0, s[34:35]
	global_load_lds_dwordx4 v[164:165], off
	s_lshl_b64 s[34:35], s[20:21], 1
	s_add_u32 s34, s34, 0xc0000
	s_addc_u32 s35, s35, 0
	s_add_u32 m0, s28, 0x4000
	v_lshl_add_u64 v[164:165], v[136:137], 0, s[34:35]
	global_load_lds_dwordx4 v[164:165], off
	s_lshl_b64 s[34:35], s[20:21], 1
	s_add_u32 s34, s34, 0x120000
	s_addc_u32 s35, s35, 0
	s_add_u32 m0, s28, 0x6000
	v_lshl_add_u64 v[164:165], v[136:137], 0, s[34:35]
	global_load_lds_dwordx4 v[164:165], off
	s_add_u32 s34, s4, 0x7c0080
	s_addc_u32 s35, s5, 0
	s_add_u32 m0, s28, 0x8000
	v_lshl_add_u64 v[164:165], v[138:139], 0, s[34:35]
	global_load_lds_dwordx4 v[164:165], off
	s_add_u32 s34, s4, s68
	s_addc_u32 s35, s5, s69
	s_add_u32 m0, s28, 0xa000
	v_lshl_add_u64 v[164:165], v[138:139], 0, s[34:35]
	global_load_lds_dwordx4 v[164:165], off
	s_add_u32 s34, s4, s80
	s_addc_u32 s35, s5, s81
	s_add_u32 m0, s28, 0xc000
	v_lshl_add_u64 v[164:165], v[138:139], 0, s[34:35]
	global_load_lds_dwordx4 v[164:165], off
	s_add_u32 s34, s4, 0x880080
	s_addc_u32 s35, s5, 0
	s_add_u32 m0, s28, 0xe000
	v_lshl_add_u64 v[164:165], v[138:139], 0, s[34:35]
	global_load_lds_dwordx4 v[164:165], off
	v_add3_u32 v155, s15, v150, v149
	v_add_u32_e32 v155, v155, v152
	v_add3_u32 v0, s15, v147, v149
	v_add_u32_e32 v0, v0, v152
	ds_read_b128 v[208:211], v155 offset:32768
	ds_read_b128 v[212:215], v155 offset:36864
	s_waitcnt lgkmcnt(5)
	v_mfma_f32_32x32x16_bf16 v[114:129], v[192:195], v[156:159], v[114:129]
	v_mfma_f32_32x32x16_bf16 v[98:113], v[192:195], v[160:163], v[98:113]
	ds_read_b128 v[192:195], v0
	s_waitcnt lgkmcnt(5)
	v_mfma_f32_32x32x16_bf16 v[82:97], v[196:199], v[156:159], v[82:97]
	v_mfma_f32_32x32x16_bf16 v[66:81], v[196:199], v[160:163], v[66:81]
	ds_read_b128 v[196:199], v0 offset:4096
	s_waitcnt lgkmcnt(5)
	v_mfma_f32_32x32x16_bf16 v[50:65], v[200:203], v[156:159], v[50:65]
	v_mfma_f32_32x32x16_bf16 v[34:49], v[200:203], v[160:163], v[34:49]
	ds_read_b128 v[200:203], v0 offset:8192
	s_waitcnt lgkmcnt(5)
	v_mfma_f32_32x32x16_bf16 v[18:33], v[204:207], v[156:159], v[18:33]
	v_mfma_f32_32x32x16_bf16 v[2:17], v[204:207], v[160:163], v[2:17]
	ds_read_b128 v[204:207], v0 offset:12288
	v_add3_u32 v155, s15, v150, v149
	v_add_u32_e32 v155, v155, v153
	v_add3_u32 v0, s15, v147, v149
	v_add_u32_e32 v0, v0, v153
	ds_read_b128 v[156:159], v155 offset:32768
	ds_read_b128 v[160:163], v155 offset:36864
	s_waitcnt lgkmcnt(5)
	v_mfma_f32_32x32x16_bf16 v[114:129], v[192:195], v[208:211], v[114:129]
	v_mfma_f32_32x32x16_bf16 v[98:113], v[192:195], v[212:215], v[98:113]
	ds_read_b128 v[192:195], v0
	s_waitcnt lgkmcnt(5)
	v_mfma_f32_32x32x16_bf16 v[82:97], v[196:199], v[208:211], v[82:97]
	v_mfma_f32_32x32x16_bf16 v[66:81], v[196:199], v[212:215], v[66:81]
	ds_read_b128 v[196:199], v0 offset:4096
	s_waitcnt lgkmcnt(5)
	v_mfma_f32_32x32x16_bf16 v[50:65], v[200:203], v[208:211], v[50:65]
	v_mfma_f32_32x32x16_bf16 v[34:49], v[200:203], v[212:215], v[34:49]
	ds_read_b128 v[200:203], v0 offset:8192
	s_waitcnt lgkmcnt(5)
	v_mfma_f32_32x32x16_bf16 v[18:33], v[204:207], v[208:211], v[18:33]
	v_mfma_f32_32x32x16_bf16 v[2:17], v[204:207], v[212:215], v[2:17]
	ds_read_b128 v[204:207], v0 offset:12288
	v_add3_u32 v155, s15, v150, v149
	v_add_u32_e32 v155, v155, v154
	v_add3_u32 v0, s15, v147, v149
	v_add_u32_e32 v0, v0, v154
	ds_read_b128 v[208:211], v155 offset:32768
	ds_read_b128 v[212:215], v155 offset:36864
	s_waitcnt lgkmcnt(5)
	v_mfma_f32_32x32x16_bf16 v[114:129], v[192:195], v[156:159], v[114:129]
	v_mfma_f32_32x32x16_bf16 v[98:113], v[192:195], v[160:163], v[98:113]
	ds_read_b128 v[192:195], v0
	s_waitcnt lgkmcnt(5)
	v_mfma_f32_32x32x16_bf16 v[82:97], v[196:199], v[156:159], v[82:97]
	v_mfma_f32_32x32x16_bf16 v[66:81], v[196:199], v[160:163], v[66:81]
	ds_read_b128 v[196:199], v0 offset:4096
	s_waitcnt lgkmcnt(5)
	v_mfma_f32_32x32x16_bf16 v[50:65], v[200:203], v[156:159], v[50:65]
	v_mfma_f32_32x32x16_bf16 v[34:49], v[200:203], v[160:163], v[34:49]
	ds_read_b128 v[200:203], v0 offset:8192
	s_waitcnt lgkmcnt(5)
	v_mfma_f32_32x32x16_bf16 v[18:33], v[204:207], v[156:159], v[18:33]
	v_mfma_f32_32x32x16_bf16 v[2:17], v[204:207], v[160:163], v[2:17]
	ds_read_b128 v[204:207], v0 offset:12288
	s_waitcnt lgkmcnt(3)
	v_mfma_f32_32x32x16_bf16 v[114:129], v[192:195], v[208:211], v[114:129]
	v_mfma_f32_32x32x16_bf16 v[98:113], v[192:195], v[212:215], v[98:113]
	s_waitcnt lgkmcnt(2)
	v_mfma_f32_32x32x16_bf16 v[82:97], v[196:199], v[208:211], v[82:97]
	v_mfma_f32_32x32x16_bf16 v[66:81], v[196:199], v[212:215], v[66:81]
	s_waitcnt lgkmcnt(0)
	s_waitcnt vmcnt(0)
	s_barrier
; template <int EPI, int AMAP, int KOFFMODE, int K>
; __device__ __forceinline__ void gemm_phase(unsigned char* smem, const bf16_t* A, int lda, const bf16_t* Bt, int NT, const EpiArgs& ea) {
;     ...
;         for (int kt = 0; kt < nk; ++kt) {
;             if (kt + 1 < nk) GEMM_DMA(m0, n0, kt + 1, cur ^ 1);
;             else if (have_next) GEMM_DMA(m0n, n0n, 0, cur ^ 1);
;             const unsigned char* Ac = smem + cur * STGB + (wm * 128 + l31) * 128;
;             const unsigned char* Bc = smem + cur * STGB + 32768 + (wn * 64 + l31) * 128;
;             bf16x8 fa[2][4], fb[2][2];
;             fb[0][0] = *(const bf16x8*)(Bc + (((0) ^ yz) & 7) * 16);
;             fb[0][1] = *(const bf16x8*)(Bc + 32 * 128 + (((0) ^ yz) & 7) * 16);
; #pragma unroll
;             for (int i = 0; i < 4; ++i) fa[0][i] = *(const bf16x8*)(Ac + i * 32 * 128 + (((0) ^ yz) & 7) * 16);
; #pragma unroll
;             for (int s = 0; s < 4; ++s) {
;                 if (s < 3) {
;                     const int o_ = (((2 * (s + 1)) ^ yz) & 7) * 16;
;                     fb[(s + 1) & 1][0] = *(const bf16x8*)(Bc + o_);
;                     fb[(s + 1) & 1][1] = *(const bf16x8*)(Bc + 32 * 128 + o_);
; #pragma unroll
;                     for (int i = 0; i < 4; ++i) fa[(s + 1) & 1][i] = *(const bf16x8*)(Ac + i * 32 * 128 + o_);
;                 }
; #pragma unroll
;                 for (int i = 0; i < 4; ++i) {
;                     acc[i][0] = __builtin_amdgcn_mfma_f32_32x32x16_bf16(fa[s & 1][i], fb[s & 1][0], acc[i][0], 0, 0, 0);
;                     acc[i][1] = __builtin_amdgcn_mfma_f32_32x32x16_bf16(fa[s & 1][i], fb[s & 1][1], acc[i][1], 0, 0, 0);
;                 }
;                 __builtin_amdgcn_sched_barrier(0);
;             }
;             if (kt + 1 < nk) asm volatile("s_waitcnt vmcnt(0)" ::: "memory");
;             __builtin_amdgcn_s_barrier();
;             cur ^= 1;
;         }
	v_add3_u32 v155, s14, v150, v149
	v_add_u32_e32 v155, v155, v151
	v_add3_u32 v0, s14, v147, v149
	v_add_u32_e32 v0, v0, v151
	ds_read_b128 v[156:159], v155 offset:32768
	ds_read_b128 v[160:163], v155 offset:36864
	ds_read_b128 v[192:195], v0
	ds_read_b128 v[196:199], v0 offset:4096
	v_mfma_f32_32x32x16_bf16 v[50:65], v[200:203], v[208:211], v[50:65]
	v_mfma_f32_32x32x16_bf16 v[34:49], v[200:203], v[212:215], v[34:49]
	ds_read_b128 v[200:203], v0 offset:8192
	v_mfma_f32_32x32x16_bf16 v[18:33], v[204:207], v[208:211], v[18:33]
	v_mfma_f32_32x32x16_bf16 v[2:17], v[204:207], v[212:215], v[2:17]
	ds_read_b128 v[204:207], v0 offset:12288
	s_xor_b32 s15, s9, 1
	s_add_u32 s4, s4, 0x80
	s_addc_u32 s5, s5, 0
	s_add_i32 s12, s12, 1
	s_add_i32 s13, s13, 64
	s_mov_b64 s[34:35], 0x60000
	s_cmpk_eq_i32 s4, 0xf80
	s_cbranch_scc0 .LBB0_927
	s_waitcnt lgkmcnt(0)
	v_writelane_b32 v251, s20, 18
	s_andn2_b64 vcc, exec, s[2:3]
	s_lshl_b32 s2, s15, 16
	v_writelane_b32 v251, s21, 19
	s_cbranch_vccnz .LBB0_919
	v_add_u32_e32 v0, s8, v142
	s_movk_i32 s3, 0x1800
	v_mad_i64_i32 v[138:139], s[4:5], v0, s3, v[130:131]
	s_xor_b32 s3, s2, 0x10000
	v_add_u32_e32 v136, s7, v142
	v_add_u32_e32 v0, s3, v143
	v_ashrrev_i32_e32 v137, 31, v136
	v_add_u32_e32 v155, 0x8000, v0
	v_readfirstlane_b32 s3, v0
	v_lshlrev_b64 v[136:137], 12, v[136:137]
	s_mov_b32 m0, s3
	v_readfirstlane_b32 s3, v155
	v_add_u32_e32 v155, 0x2000, v0
	v_lshl_add_u64 v[136:137], v[132:133], 0, v[136:137]
	global_load_lds_dwordx4 v[138:139], off
	s_mov_b32 m0, s3
	v_readfirstlane_b32 s3, v155
	v_add_u32_e32 v155, 0xa000, v0
	global_load_lds_dwordx4 v[136:137], off
	v_lshl_add_u64 v[156:157], v[138:139], 0, s[34:35]
	s_mov_b32 m0, s3
	s_mov_b64 s[4:5], 0x40000
	v_readfirstlane_b32 s3, v155
	v_add_u32_e32 v155, 0x4000, v0
	global_load_lds_dwordx4 v[156:157], off
	v_lshl_add_u64 v[156:157], v[136:137], 0, s[4:5]
	s_mov_b32 m0, s3
	s_mov_b64 s[4:5], 0xc0000
	v_readfirstlane_b32 s3, v155
	v_add_u32_e32 v155, 0xc000, v0
	global_load_lds_dwordx4 v[156:157], off
	v_lshl_add_u64 v[156:157], v[138:139], 0, s[4:5]
	s_mov_b32 m0, s3
	s_mov_b64 s[12:13], 0x80000
	v_readfirstlane_b32 s3, v155
	v_add_u32_e32 v155, 0x6000, v0
	global_load_lds_dwordx4 v[156:157], off
	v_lshl_add_u64 v[156:157], v[136:137], 0, s[12:13]
	s_mov_b32 m0, s3
	s_mov_b64 s[12:13], 0x120000
	v_readfirstlane_b32 s3, v155
	v_add_u32_e32 v0, 0xe000, v0
	global_load_lds_dwordx4 v[156:157], off
	v_lshl_add_u64 v[138:139], v[138:139], 0, s[12:13]
	s_mov_b32 m0, s3
	v_readfirstlane_b32 s3, v0
	global_load_lds_dwordx4 v[138:139], off
	v_lshl_add_u64 v[136:137], v[136:137], 0, s[4:5]
	s_mov_b32 m0, s3
	s_nop 0
	global_load_lds_dwordx4 v[136:137], off
	s_branch .LBB0_919

; template <int EPI, int AMAP, int KOFFMODE, int K>
; __device__ __forceinline__ void gemm_phase(unsigned char* smem, const bf16_t* A, int lda, const bf16_t* Bt, int NT, const EpiArgs& ea) {
;     ...
;         for (int kt = 0; kt < nk; ++kt) {
;             if (kt + 1 < nk) GEMM_DMA(m0, n0, kt + 1, cur ^ 1);
;             else if (have_next) GEMM_DMA(m0n, n0n, 0, cur ^ 1);
;             const unsigned char* Ac = smem + cur * STGB + (wm * 128 + l31) * 128;
;             const unsigned char* Bc = smem + cur * STGB + 32768 + (wn * 64 + l31) * 128;
;             bf16x8 fa[2][4], fb[2][2];
;             fb[0][0] = *(const bf16x8*)(Bc + (((0) ^ yz) & 7) * 16);
;             fb[0][1] = *(const bf16x8*)(Bc + 32 * 128 + (((0) ^ yz) & 7) * 16);
; #pragma unroll
;             for (int i = 0; i < 4; ++i) fa[0][i] = *(const bf16x8*)(Ac + i * 32 * 128 + (((0) ^ yz) & 7) * 16);
; #pragma unroll
;             for (int s = 0; s < 4; ++s) {
;                 if (s < 3) {
;                     const int o_ = (((2 * (s + 1)) ^ yz) & 7) * 16;
;                     fb[(s + 1) & 1][0] = *(const bf16x8*)(Bc + o_);
;                     fb[(s + 1) & 1][1] = *(const bf16x8*)(Bc + 32 * 128 + o_);
; #pragma unroll
;                     for (int i = 0; i < 4; ++i) fa[(s + 1) & 1][i] = *(const bf16x8*)(Ac + i * 32 * 128 + o_);
;                 }
; #pragma unroll
;                 for (int i = 0; i < 4; ++i) {
;                     acc[i][0] = __builtin_amdgcn_mfma_f32_32x32x16_bf16(fa[s & 1][i], fb[s & 1][0], acc[i][0], 0, 0, 0);
;                     acc[i][1] = __builtin_amdgcn_mfma_f32_32x32x16_bf16(fa[s & 1][i], fb[s & 1][1], acc[i][1], 0, 0, 0);
;                 }
;                 __builtin_amdgcn_sched_barrier(0);
;             }
;             if (kt + 1 < nk) asm volatile("s_waitcnt vmcnt(0)" ::: "memory");
;             __builtin_amdgcn_s_barrier();
.LBB0_1032:
	s_mov_b32 s11, s15
	s_lshl_b32 s15, s11, 16
	s_xor_b32 s14, s15, 0x10000
	v_readfirstlane_b32 s28, v144
	s_nop 0
	s_add_u32 s28, s28, s14
	s_add_u32 s34, s4, s20
	s_addc_u32 s35, s5, s21
	s_mov_b32 m0, s28
	v_lshl_add_u64 v[164:165], v[136:137], 0, s[34:35]
	global_load_lds_dwordx4 v[164:165], off
	s_add_u32 s34, s4, vcc_lo
	s_addc_u32 s35, s5, vcc_hi
	s_add_u32 m0, s28, 0x2000
	v_lshl_add_u64 v[164:165], v[136:137], 0, s[34:35]
	global_load_lds_dwordx4 v[164:165], off
	s_add_u32 s34, s4, s68
	s_addc_u32 s35, s5, s69
	s_add_u32 m0, s28, 0x4000
	v_lshl_add_u64 v[164:165], v[136:137], 0, s[34:35]
	global_load_lds_dwordx4 v[164:165], off
	s_add_u32 s34, s4, s88
	s_addc_u32 s35, s5, s89
	s_add_u32 m0, s28, 0x6000
	v_lshl_add_u64 v[164:165], v[136:137], 0, s[34:35]
	global_load_lds_dwordx4 v[164:165], off
	s_add_u32 s34, s4, 0xe00080
	s_addc_u32 s35, s5, 0
	s_add_u32 m0, s28, 0x8000
	v_lshl_add_u64 v[164:165], v[138:139], 0, s[34:35]
	global_load_lds_dwordx4 v[164:165], off
	s_add_u32 s34, s4, 0xe20080
	s_addc_u32 s35, s5, 0
	s_add_u32 m0, s28, 0xa000
	v_lshl_add_u64 v[164:165], v[138:139], 0, s[34:35]
	global_load_lds_dwordx4 v[164:165], off
	s_add_u32 s34, s4, 0xe40080
	s_addc_u32 s35, s5, 0
	s_add_u32 m0, s28, 0xc000
	v_lshl_add_u64 v[164:165], v[138:139], 0, s[34:35]
	global_load_lds_dwordx4 v[164:165], off
	s_add_u32 s34, s4, 0xe60080
	s_addc_u32 s35, s5, 0
	s_add_u32 m0, s28, 0xe000
	v_lshl_add_u64 v[164:165], v[138:139], 0, s[34:35]
	global_load_lds_dwordx4 v[164:165], off
	v_add3_u32 v191, s15, v151, v150
	v_add_u32_e32 v191, v191, v153
	v_add3_u32 v0, s15, v149, v150
	v_add_u32_e32 v0, v0, v153
	ds_read_b128 v[208:211], v191 offset:32768
	ds_read_b128 v[212:215], v191 offset:36864
	s_waitcnt lgkmcnt(5)
	v_mfma_f32_32x32x16_bf16 v[114:129], v[192:195], v[156:159], v[114:129]
	v_mfma_f32_32x32x16_bf16 v[98:113], v[192:195], v[160:163], v[98:113]
	ds_read_b128 v[192:195], v0
	s_waitcnt lgkmcnt(5)
	v_mfma_f32_32x32x16_bf16 v[82:97], v[196:199], v[156:159], v[82:97]
	v_mfma_f32_32x32x16_bf16 v[66:81], v[196:199], v[160:163], v[66:81]
	ds_read_b128 v[196:199], v0 offset:4096
	s_waitcnt lgkmcnt(5)
	v_mfma_f32_32x32x16_bf16 v[50:65], v[200:203], v[156:159], v[50:65]
	v_mfma_f32_32x32x16_bf16 v[34:49], v[200:203], v[160:163], v[34:49]
	ds_read_b128 v[200:203], v0 offset:8192
	s_waitcnt lgkmcnt(5)
	v_mfma_f32_32x32x16_bf16 v[18:33], v[204:207], v[156:159], v[18:33]
	v_mfma_f32_32x32x16_bf16 v[2:17], v[204:207], v[160:163], v[2:17]
	ds_read_b128 v[204:207], v0 offset:12288
	v_add3_u32 v191, s15, v151, v150
	v_add_u32_e32 v191, v191, v154
	v_add3_u32 v0, s15, v149, v150
	v_add_u32_e32 v0, v0, v154
	ds_read_b128 v[156:159], v191 offset:32768
	ds_read_b128 v[160:163], v191 offset:36864
	s_waitcnt lgkmcnt(5)
	v_mfma_f32_32x32x16_bf16 v[114:129], v[192:195], v[208:211], v[114:129]
	v_mfma_f32_32x32x16_bf16 v[98:113], v[192:195], v[212:215], v[98:113]
	ds_read_b128 v[192:195], v0
	s_waitcnt lgkmcnt(5)
	v_mfma_f32_32x32x16_bf16 v[82:97], v[196:199], v[208:211], v[82:97]
	v_mfma_f32_32x32x16_bf16 v[66:81], v[196:199], v[212:215], v[66:81]
	ds_read_b128 v[196:199], v0 offset:4096
	s_waitcnt lgkmcnt(5)
	v_mfma_f32_32x32x16_bf16 v[50:65], v[200:203], v[208:211], v[50:65]
	v_mfma_f32_32x32x16_bf16 v[34:49], v[200:203], v[212:215], v[34:49]
	ds_read_b128 v[200:203], v0 offset:8192
	s_waitcnt lgkmcnt(5)
	v_mfma_f32_32x32x16_bf16 v[18:33], v[204:207], v[208:211], v[18:33]
	v_mfma_f32_32x32x16_bf16 v[2:17], v[204:207], v[212:215], v[2:17]
	ds_read_b128 v[204:207], v0 offset:12288
	v_add3_u32 v191, s15, v151, v150
	v_add_u32_e32 v191, v191, v155
	v_add3_u32 v0, s15, v149, v150
	v_add_u32_e32 v0, v0, v155
	ds_read_b128 v[208:211], v191 offset:32768
	ds_read_b128 v[212:215], v191 offset:36864
	s_waitcnt lgkmcnt(5)
	v_mfma_f32_32x32x16_bf16 v[114:129], v[192:195], v[156:159], v[114:129]
	v_mfma_f32_32x32x16_bf16 v[98:113], v[192:195], v[160:163], v[98:113]
	ds_read_b128 v[192:195], v0
	s_waitcnt lgkmcnt(5)
	v_mfma_f32_32x32x16_bf16 v[82:97], v[196:199], v[156:159], v[82:97]
	v_mfma_f32_32x32x16_bf16 v[66:81], v[196:199], v[160:163], v[66:81]
	ds_read_b128 v[196:199], v0 offset:4096
	s_waitcnt lgkmcnt(5)
	v_mfma_f32_32x32x16_bf16 v[50:65], v[200:203], v[156:159], v[50:65]
	v_mfma_f32_32x32x16_bf16 v[34:49], v[200:203], v[160:163], v[34:49]
	ds_read_b128 v[200:203], v0 offset:8192
	s_waitcnt lgkmcnt(5)
	v_mfma_f32_32x32x16_bf16 v[18:33], v[204:207], v[156:159], v[18:33]
	v_mfma_f32_32x32x16_bf16 v[2:17], v[204:207], v[160:163], v[2:17]
	ds_read_b128 v[204:207], v0 offset:12288
	s_waitcnt lgkmcnt(3)
	v_mfma_f32_32x32x16_bf16 v[114:129], v[192:195], v[208:211], v[114:129]
	v_mfma_f32_32x32x16_bf16 v[98:113], v[192:195], v[212:215], v[98:113]
	s_waitcnt lgkmcnt(2)
	v_mfma_f32_32x32x16_bf16 v[82:97], v[196:199], v[208:211], v[82:97]
	v_mfma_f32_32x32x16_bf16 v[66:81], v[196:199], v[212:215], v[66:81]
	s_waitcnt lgkmcnt(0)
	s_waitcnt vmcnt(0)
	s_barrier
; template <int EPI, int AMAP, int KOFFMODE, int K>
; __device__ __forceinline__ void gemm_phase(unsigned char* smem, const bf16_t* A, int lda, const bf16_t* Bt, int NT, const EpiArgs& ea) {
;     ...
;         for (int kt = 0; kt < nk; ++kt) {
;             if (kt + 1 < nk) GEMM_DMA(m0, n0, kt + 1, cur ^ 1);
;             else if (have_next) GEMM_DMA(m0n, n0n, 0, cur ^ 1);
;             const unsigned char* Ac = smem + cur * STGB + (wm * 128 + l31) * 128;
;             const unsigned char* Bc = smem + cur * STGB + 32768 + (wn * 64 + l31) * 128;
;             bf16x8 fa[2][4], fb[2][2];
;             fb[0][0] = *(const bf16x8*)(Bc + (((0) ^ yz) & 7) * 16);
;             fb[0][1] = *(const bf16x8*)(Bc + 32 * 128 + (((0) ^ yz) & 7) * 16);
; #pragma unroll
;             for (int i = 0; i < 4; ++i) fa[0][i] = *(const bf16x8*)(Ac + i * 32 * 128 + (((0) ^ yz) & 7) * 16);
; #pragma unroll
;             for (int s = 0; s < 4; ++s) {
;                 if (s < 3) {
;                     const int o_ = (((2 * (s + 1)) ^ yz) & 7) * 16;
;                     fb[(s + 1) & 1][0] = *(const bf16x8*)(Bc + o_);
;                     fb[(s + 1) & 1][1] = *(const bf16x8*)(Bc + 32 * 128 + o_);
; #pragma unroll
;                     for (int i = 0; i < 4; ++i) fa[(s + 1) & 1][i] = *(const bf16x8*)(Ac + i * 32 * 128 + o_);
;                 }
; #pragma unroll
;                 for (int i = 0; i < 4; ++i) {
;                     acc[i][0] = __builtin_amdgcn_mfma_f32_32x32x16_bf16(fa[s & 1][i], fb[s & 1][0], acc[i][0], 0, 0, 0);
;                     acc[i][1] = __builtin_amdgcn_mfma_f32_32x32x16_bf16(fa[s & 1][i], fb[s & 1][1], acc[i][1], 0, 0, 0);
;                 }
;                 __builtin_amdgcn_sched_barrier(0);
;             }
;             if (kt + 1 < nk) asm volatile("s_waitcnt vmcnt(0)" ::: "memory");
;             __builtin_amdgcn_s_barrier();
;             cur ^= 1;
;         }
	v_add3_u32 v191, s14, v151, v150
	v_add_u32_e32 v191, v191, v152
	v_add3_u32 v0, s14, v149, v150
	v_add_u32_e32 v0, v0, v152
	ds_read_b128 v[156:159], v191 offset:32768
	ds_read_b128 v[160:163], v191 offset:36864
	ds_read_b128 v[192:195], v0
	ds_read_b128 v[196:199], v0 offset:4096
	v_mfma_f32_32x32x16_bf16 v[50:65], v[200:203], v[208:211], v[50:65]
	v_mfma_f32_32x32x16_bf16 v[34:49], v[200:203], v[212:215], v[34:49]
	ds_read_b128 v[200:203], v0 offset:8192
	v_mfma_f32_32x32x16_bf16 v[18:33], v[204:207], v[208:211], v[18:33]
	v_mfma_f32_32x32x16_bf16 v[2:17], v[204:207], v[212:215], v[2:17]
	ds_read_b128 v[204:207], v0 offset:12288
	s_xor_b32 s15, s11, 1
	s_add_u32 s4, s4, 0x80
	s_addc_u32 s5, s5, 0
	s_cmpk_eq_i32 s4, 0x780
	s_cbranch_scc0 .LBB0_1032
	s_waitcnt lgkmcnt(0)
	s_andn2_b64 vcc, exec, s[2:3]
	s_lshl_b32 s2, s15, 16
	s_cbranch_vccnz .LBB0_1024
	v_add_u32_e32 v136, s10, v143
	s_xor_b32 s3, s2, 0x10000
	v_ashrrev_i32_e32 v137, 31, v136
	v_add_u32_e32 v138, s9, v143
	v_add_u32_e32 v0, s3, v144
	v_lshlrev_b64 v[136:137], 11, v[136:137]
	v_ashrrev_i32_e32 v139, 31, v138
	v_add_u32_e32 v156, 0x8000, v0
	v_readfirstlane_b32 s3, v0
	v_lshlrev_b64 v[138:139], 11, v[138:139]
	v_lshl_add_u64 v[136:137], v[130:131], 0, v[136:137]
	s_mov_b32 m0, s3
	v_readfirstlane_b32 s3, v156
	v_add_u32_e32 v158, 0x2000, v0
	v_lshl_add_u64 v[138:139], v[132:133], 0, v[138:139]
	global_load_lds_dwordx4 v[136:137], off
	s_mov_b32 m0, s3
	s_mov_b64 s[4:5], 0x20000
	v_readfirstlane_b32 s3, v158
	v_add_u32_e32 v158, 0xa000, v0
	global_load_lds_dwordx4 v[138:139], off
	v_lshl_add_u64 v[156:157], v[136:137], 0, s[4:5]
	s_mov_b32 m0, s3
	v_readfirstlane_b32 s3, v158
	v_add_u32_e32 v158, 0x4000, v0
	global_load_lds_dwordx4 v[156:157], off
	v_lshl_add_u64 v[156:157], v[138:139], 0, s[4:5]
	s_mov_b32 m0, s3
	s_mov_b64 s[4:5], 0x40000
	v_readfirstlane_b32 s3, v158
	v_add_u32_e32 v158, 0xc000, v0
	global_load_lds_dwordx4 v[156:157], off
	v_lshl_add_u64 v[156:157], v[136:137], 0, s[4:5]
	s_mov_b32 m0, s3
	v_readfirstlane_b32 s3, v158
	global_load_lds_dwordx4 v[156:157], off
	v_lshl_add_u64 v[156:157], v[138:139], 0, s[4:5]
	s_mov_b32 m0, s3
	s_mov_b64 s[4:5], 0x60000
	global_load_lds_dwordx4 v[156:157], off
	v_add_u32_e32 v156, 0x6000, v0
	v_add_u32_e32 v0, 0xe000, v0
	v_readfirstlane_b32 s3, v156
	v_lshl_add_u64 v[136:137], v[136:137], 0, s[4:5]
	s_mov_b32 m0, s3
	v_readfirstlane_b32 s3, v0
	global_load_lds_dwordx4 v[136:137], off
	v_lshl_add_u64 v[136:137], v[138:139], 0, s[4:5]
	s_mov_b32 m0, s3
	s_nop 0
	global_load_lds_dwordx4 v[136:137], off
	s_branch .LBB0_1024

; template <int EPI, int AMAP, int KOFFMODE, int K>
; __device__ __forceinline__ void gemm_phase(unsigned char* smem, const bf16_t* A, int lda, const bf16_t* Bt, int NT, const EpiArgs& ea) {
;     ...
;         for (int kt = 0; kt < nk; ++kt) {
;             if (kt + 1 < nk) GEMM_DMA(m0, n0, kt + 1, cur ^ 1);
;             else if (have_next) GEMM_DMA(m0n, n0n, 0, cur ^ 1);
;             const unsigned char* Ac = smem + cur * STGB + (wm * 128 + l31) * 128;
;             const unsigned char* Bc = smem + cur * STGB + 32768 + (wn * 64 + l31) * 128;
;             bf16x8 fa[2][4], fb[2][2];
;             fb[0][0] = *(const bf16x8*)(Bc + (((0) ^ yz) & 7) * 16);
;             fb[0][1] = *(const bf16x8*)(Bc + 32 * 128 + (((0) ^ yz) & 7) * 16);
; #pragma unroll
;             for (int i = 0; i < 4; ++i) fa[0][i] = *(const bf16x8*)(Ac + i * 32 * 128 + (((0) ^ yz) & 7) * 16);
; #pragma unroll
;             for (int s = 0; s < 4; ++s) {
;                 if (s < 3) {
;                     const int o_ = (((2 * (s + 1)) ^ yz) & 7) * 16;
;                     fb[(s + 1) & 1][0] = *(const bf16x8*)(Bc + o_);
;                     fb[(s + 1) & 1][1] = *(const bf16x8*)(Bc + 32 * 128 + o_);
; #pragma unroll
;                     for (int i = 0; i < 4; ++i) fa[(s + 1) & 1][i] = *(const bf16x8*)(Ac + i * 32 * 128 + o_);
;                 }
; #pragma unroll
;                 for (int i = 0; i < 4; ++i) {
;                     acc[i][0] = __builtin_amdgcn_mfma_f32_32x32x16_bf16(fa[s & 1][i], fb[s & 1][0], acc[i][0], 0, 0, 0);
;                     acc[i][1] = __builtin_amdgcn_mfma_f32_32x32x16_bf16(fa[s & 1][i], fb[s & 1][1], acc[i][1], 0, 0, 0);
;                 }
;                 __builtin_amdgcn_sched_barrier(0);
;             }
;             if (kt + 1 < nk) asm volatile("s_waitcnt vmcnt(0)" ::: "memory");
;             __builtin_amdgcn_s_barrier();
.LBB0_1161:
	s_mov_b32 s13, s34
	s_lshl_b32 s36, s13, 16
	s_xor_b32 s28, s36, 0x10000
	v_readfirstlane_b32 vcc_lo, v144
	s_nop 0
	s_add_u32 vcc_lo, vcc_lo, s28
	s_add_u32 s34, s8, 0x4100080
	s_addc_u32 s35, s9, 0
	s_mov_b32 m0, vcc_lo
	v_lshl_add_u64 v[164:165], v[136:137], 0, s[34:35]
	global_load_lds_dwordx4 v[164:165], off
	s_add_u32 s34, s8, 0x4158080
	s_addc_u32 s35, s9, 0
	s_add_u32 m0, vcc_lo, 0x2000
	v_lshl_add_u64 v[164:165], v[136:137], 0, s[34:35]
	global_load_lds_dwordx4 v[164:165], off
	s_add_u32 s34, s8, 0x41b0080
	s_addc_u32 s35, s9, 0
	s_add_u32 m0, vcc_lo, 0x4000
	v_lshl_add_u64 v[164:165], v[136:137], 0, s[34:35]
	global_load_lds_dwordx4 v[164:165], off
	s_add_u32 s34, s8, 0x4208080
	s_addc_u32 s35, s9, 0
	s_add_u32 m0, vcc_lo, 0x6000
	v_lshl_add_u64 v[164:165], v[136:137], 0, s[34:35]
	global_load_lds_dwordx4 v[164:165], off
	s_add_u32 s34, s8, 0x1900080
	s_addc_u32 s35, s9, 0
	s_add_u32 m0, vcc_lo, 0x8000
	v_lshl_add_u64 v[164:165], v[138:139], 0, s[34:35]
	global_load_lds_dwordx4 v[164:165], off
	s_add_u32 s34, s8, 0x1958080
	s_addc_u32 s35, s9, 0
	s_add_u32 m0, vcc_lo, 0xa000
	v_lshl_add_u64 v[164:165], v[138:139], 0, s[34:35]
	global_load_lds_dwordx4 v[164:165], off
	s_add_u32 s34, s8, 0x19b0080
	s_addc_u32 s35, s9, 0
	s_add_u32 m0, vcc_lo, 0xc000
	v_lshl_add_u64 v[164:165], v[138:139], 0, s[34:35]
	global_load_lds_dwordx4 v[164:165], off
	s_add_u32 s34, s8, 0x1a08080
	s_addc_u32 s35, s9, 0
	s_add_u32 m0, vcc_lo, 0xe000
	v_lshl_add_u64 v[164:165], v[138:139], 0, s[34:35]
	global_load_lds_dwordx4 v[164:165], off
	v_add3_u32 v191, s36, v151, v150
	v_add_u32_e32 v191, v191, v153
	v_add3_u32 v0, s36, v149, v150
	v_add_u32_e32 v0, v0, v153
	ds_read_b128 v[208:211], v191 offset:32768
	ds_read_b128 v[212:215], v191 offset:36864
	s_waitcnt lgkmcnt(5)
	v_mfma_f32_32x32x16_bf16 v[114:129], v[192:195], v[156:159], v[114:129]
	v_mfma_f32_32x32x16_bf16 v[98:113], v[192:195], v[160:163], v[98:113]
	ds_read_b128 v[192:195], v0
	s_waitcnt lgkmcnt(5)
	v_mfma_f32_32x32x16_bf16 v[82:97], v[196:199], v[156:159], v[82:97]
	v_mfma_f32_32x32x16_bf16 v[66:81], v[196:199], v[160:163], v[66:81]
	ds_read_b128 v[196:199], v0 offset:4096
	s_waitcnt lgkmcnt(5)
	v_mfma_f32_32x32x16_bf16 v[50:65], v[200:203], v[156:159], v[50:65]
	v_mfma_f32_32x32x16_bf16 v[34:49], v[200:203], v[160:163], v[34:49]
	ds_read_b128 v[200:203], v0 offset:8192
	s_waitcnt lgkmcnt(5)
	v_mfma_f32_32x32x16_bf16 v[18:33], v[204:207], v[156:159], v[18:33]
	v_mfma_f32_32x32x16_bf16 v[2:17], v[204:207], v[160:163], v[2:17]
	ds_read_b128 v[204:207], v0 offset:12288
	v_add3_u32 v191, s36, v151, v150
	v_add_u32_e32 v191, v191, v154
	v_add3_u32 v0, s36, v149, v150
	v_add_u32_e32 v0, v0, v154
	ds_read_b128 v[156:159], v191 offset:32768
	ds_read_b128 v[160:163], v191 offset:36864
	s_waitcnt lgkmcnt(5)
	v_mfma_f32_32x32x16_bf16 v[114:129], v[192:195], v[208:211], v[114:129]
	v_mfma_f32_32x32x16_bf16 v[98:113], v[192:195], v[212:215], v[98:113]
	ds_read_b128 v[192:195], v0
	s_waitcnt lgkmcnt(5)
	v_mfma_f32_32x32x16_bf16 v[82:97], v[196:199], v[208:211], v[82:97]
	v_mfma_f32_32x32x16_bf16 v[66:81], v[196:199], v[212:215], v[66:81]
	ds_read_b128 v[196:199], v0 offset:4096
	s_waitcnt lgkmcnt(5)
	v_mfma_f32_32x32x16_bf16 v[50:65], v[200:203], v[208:211], v[50:65]
	v_mfma_f32_32x32x16_bf16 v[34:49], v[200:203], v[212:215], v[34:49]
	ds_read_b128 v[200:203], v0 offset:8192
	s_waitcnt lgkmcnt(5)
	v_mfma_f32_32x32x16_bf16 v[18:33], v[204:207], v[208:211], v[18:33]
	v_mfma_f32_32x32x16_bf16 v[2:17], v[204:207], v[212:215], v[2:17]
	ds_read_b128 v[204:207], v0 offset:12288
	v_add3_u32 v191, s36, v151, v150
	v_add_u32_e32 v191, v191, v155
	v_add3_u32 v0, s36, v149, v150
	v_add_u32_e32 v0, v0, v155
	ds_read_b128 v[208:211], v191 offset:32768
	ds_read_b128 v[212:215], v191 offset:36864
	s_waitcnt lgkmcnt(5)
	v_mfma_f32_32x32x16_bf16 v[114:129], v[192:195], v[156:159], v[114:129]
	v_mfma_f32_32x32x16_bf16 v[98:113], v[192:195], v[160:163], v[98:113]
	ds_read_b128 v[192:195], v0
	s_waitcnt lgkmcnt(5)
	v_mfma_f32_32x32x16_bf16 v[82:97], v[196:199], v[156:159], v[82:97]
	v_mfma_f32_32x32x16_bf16 v[66:81], v[196:199], v[160:163], v[66:81]
	ds_read_b128 v[196:199], v0 offset:4096
	s_waitcnt lgkmcnt(5)
	v_mfma_f32_32x32x16_bf16 v[50:65], v[200:203], v[156:159], v[50:65]
	v_mfma_f32_32x32x16_bf16 v[34:49], v[200:203], v[160:163], v[34:49]
	ds_read_b128 v[200:203], v0 offset:8192
	s_waitcnt lgkmcnt(5)
	v_mfma_f32_32x32x16_bf16 v[18:33], v[204:207], v[156:159], v[18:33]
	v_mfma_f32_32x32x16_bf16 v[2:17], v[204:207], v[160:163], v[2:17]
	ds_read_b128 v[204:207], v0 offset:12288
	s_waitcnt lgkmcnt(3)
	v_mfma_f32_32x32x16_bf16 v[114:129], v[192:195], v[208:211], v[114:129]
	v_mfma_f32_32x32x16_bf16 v[98:113], v[192:195], v[212:215], v[98:113]
	s_waitcnt lgkmcnt(2)
	v_mfma_f32_32x32x16_bf16 v[82:97], v[196:199], v[208:211], v[82:97]
	v_mfma_f32_32x32x16_bf16 v[66:81], v[196:199], v[212:215], v[66:81]
	s_waitcnt lgkmcnt(0)
	s_waitcnt vmcnt(0)
	s_barrier
; template <int EPI, int AMAP, int KOFFMODE, int K>
; __device__ __forceinline__ void gemm_phase(unsigned char* smem, const bf16_t* A, int lda, const bf16_t* Bt, int NT, const EpiArgs& ea) {
;     ...
;         for (int kt = 0; kt < nk; ++kt) {
;             if (kt + 1 < nk) GEMM_DMA(m0, n0, kt + 1, cur ^ 1);
;             else if (have_next) GEMM_DMA(m0n, n0n, 0, cur ^ 1);
;             const unsigned char* Ac = smem + cur * STGB + (wm * 128 + l31) * 128;
;             const unsigned char* Bc = smem + cur * STGB + 32768 + (wn * 64 + l31) * 128;
;             bf16x8 fa[2][4], fb[2][2];
;             fb[0][0] = *(const bf16x8*)(Bc + (((0) ^ yz) & 7) * 16);
;             fb[0][1] = *(const bf16x8*)(Bc + 32 * 128 + (((0) ^ yz) & 7) * 16);
; #pragma unroll
;             for (int i = 0; i < 4; ++i) fa[0][i] = *(const bf16x8*)(Ac + i * 32 * 128 + (((0) ^ yz) & 7) * 16);
; #pragma unroll
;             for (int s = 0; s < 4; ++s) {
;                 if (s < 3) {
;                     const int o_ = (((2 * (s + 1)) ^ yz) & 7) * 16;
;                     fb[(s + 1) & 1][0] = *(const bf16x8*)(Bc + o_);
;                     fb[(s + 1) & 1][1] = *(const bf16x8*)(Bc + 32 * 128 + o_);
; #pragma unroll
;                     for (int i = 0; i < 4; ++i) fa[(s + 1) & 1][i] = *(const bf16x8*)(Ac + i * 32 * 128 + o_);
;                 }
; #pragma unroll
;                 for (int i = 0; i < 4; ++i) {
;                     acc[i][0] = __builtin_amdgcn_mfma_f32_32x32x16_bf16(fa[s & 1][i], fb[s & 1][0], acc[i][0], 0, 0, 0);
;                     acc[i][1] = __builtin_amdgcn_mfma_f32_32x32x16_bf16(fa[s & 1][i], fb[s & 1][1], acc[i][1], 0, 0, 0);
;                 }
;                 __builtin_amdgcn_sched_barrier(0);
;             }
;             if (kt + 1 < nk) asm volatile("s_waitcnt vmcnt(0)" ::: "memory");
;             __builtin_amdgcn_s_barrier();
;             cur ^= 1;
;         }
	v_add3_u32 v191, s28, v151, v150
	v_add_u32_e32 v191, v191, v152
	v_add3_u32 v0, s28, v149, v150
	v_add_u32_e32 v0, v0, v152
	ds_read_b128 v[156:159], v191 offset:32768
	ds_read_b128 v[160:163], v191 offset:36864
	ds_read_b128 v[192:195], v0
	ds_read_b128 v[196:199], v0 offset:4096
	v_mfma_f32_32x32x16_bf16 v[50:65], v[200:203], v[208:211], v[50:65]
	v_mfma_f32_32x32x16_bf16 v[34:49], v[200:203], v[212:215], v[34:49]
	ds_read_b128 v[200:203], v0 offset:8192
	v_mfma_f32_32x32x16_bf16 v[18:33], v[204:207], v[208:211], v[18:33]
	v_mfma_f32_32x32x16_bf16 v[2:17], v[204:207], v[212:215], v[2:17]
	ds_read_b128 v[204:207], v0 offset:12288
	s_xor_b32 s34, s13, 1
	s_add_u32 s8, s8, 0x80
	s_addc_u32 s9, s9, 0
	s_cmpk_eq_i32 s8, 0x1580
	s_cbranch_scc0 .LBB0_1161
	s_waitcnt lgkmcnt(0)
	s_andn2_b64 vcc, exec, s[2:3]
	s_lshl_b32 s2, s34, 16
	s_cbranch_vccnz .LBB0_1153
	v_add_u32_e32 v0, s12, v143
	v_add_u32_e32 v136, s11, v143
	s_movk_i32 s3, 0x1600
	v_mad_i64_i32 v[136:137], s[8:9], v136, s3, v[132:133]
	v_mad_i64_i32 v[138:139], s[8:9], v0, s3, v[130:131]
	s_xor_b32 s3, s2, 0x10000
	v_add_u32_e32 v0, s3, v144
	v_add_u32_e32 v156, 0x8000, v0
	v_readfirstlane_b32 s3, v0
	s_mov_b32 m0, s3
	v_readfirstlane_b32 s3, v156
	v_add_u32_e32 v158, 0x2000, v0
	global_load_lds_dwordx4 v[138:139], off
	s_mov_b32 m0, s3
	s_mov_b64 s[8:9], 0x58000
	v_readfirstlane_b32 s3, v158
	v_add_u32_e32 v158, 0xa000, v0
	global_load_lds_dwordx4 v[136:137], off
	v_lshl_add_u64 v[156:157], v[138:139], 0, s[8:9]
	s_mov_b32 m0, s3
	v_readfirstlane_b32 s3, v158
	v_add_u32_e32 v158, 0x4000, v0
	global_load_lds_dwordx4 v[156:157], off
	v_lshl_add_u64 v[156:157], v[136:137], 0, s[8:9]
	s_mov_b32 m0, s3
	s_mov_b64 s[8:9], 0xb0000
	v_readfirstlane_b32 s3, v158
	v_add_u32_e32 v158, 0xc000, v0
	global_load_lds_dwordx4 v[156:157], off
	v_lshl_add_u64 v[156:157], v[138:139], 0, s[8:9]
	s_mov_b32 m0, s3
	v_readfirstlane_b32 s3, v158
	global_load_lds_dwordx4 v[156:157], off
	v_lshl_add_u64 v[156:157], v[136:137], 0, s[8:9]
	s_mov_b32 m0, s3
	s_mov_b64 s[8:9], 0x108000
	global_load_lds_dwordx4 v[156:157], off
	v_add_u32_e32 v156, 0x6000, v0
	v_add_u32_e32 v0, 0xe000, v0
	v_readfirstlane_b32 s3, v156
	v_lshl_add_u64 v[138:139], v[138:139], 0, s[8:9]
	s_mov_b32 m0, s3
	v_readfirstlane_b32 s3, v0
	global_load_lds_dwordx4 v[138:139], off
	v_lshl_add_u64 v[136:137], v[136:137], 0, s[8:9]
	s_mov_b32 m0, s3
	s_nop 0
	global_load_lds_dwordx4 v[136:137], off
	s_branch .LBB0_1153

; template <int EPI, int AMAP, int KOFFMODE, int K>
; __device__ __forceinline__ void gemm_phase(unsigned char* smem, const bf16_t* A, int lda, const bf16_t* Bt, int NT, const EpiArgs& ea) {
;     ...
;         for (int kt = 0; kt < nk; ++kt) {
;             if (kt + 1 < nk) GEMM_DMA(m0, n0, kt + 1, cur ^ 1);
;             else if (have_next) GEMM_DMA(m0n, n0n, 0, cur ^ 1);
;             const unsigned char* Ac = smem + cur * STGB + (wm * 128 + l31) * 128;
;             const unsigned char* Bc = smem + cur * STGB + 32768 + (wn * 64 + l31) * 128;
;             bf16x8 fa[2][4], fb[2][2];
;             fb[0][0] = *(const bf16x8*)(Bc + (((0) ^ yz) & 7) * 16);
;             fb[0][1] = *(const bf16x8*)(Bc + 32 * 128 + (((0) ^ yz) & 7) * 16);
; #pragma unroll
;             for (int i = 0; i < 4; ++i) fa[0][i] = *(const bf16x8*)(Ac + i * 32 * 128 + (((0) ^ yz) & 7) * 16);
; #pragma unroll
;             for (int s = 0; s < 4; ++s) {
;                 if (s < 3) {
;                     const int o_ = (((2 * (s + 1)) ^ yz) & 7) * 16;
;                     fb[(s + 1) & 1][0] = *(const bf16x8*)(Bc + o_);
;                     fb[(s + 1) & 1][1] = *(const bf16x8*)(Bc + 32 * 128 + o_);
; #pragma unroll
;                     for (int i = 0; i < 4; ++i) fa[(s + 1) & 1][i] = *(const bf16x8*)(Ac + i * 32 * 128 + o_);
;                 }
; #pragma unroll
;                 for (int i = 0; i < 4; ++i) {
;                     acc[i][0] = __builtin_amdgcn_mfma_f32_32x32x16_bf16(fa[s & 1][i], fb[s & 1][0], acc[i][0], 0, 0, 0);
;                     acc[i][1] = __builtin_amdgcn_mfma_f32_32x32x16_bf16(fa[s & 1][i], fb[s & 1][1], acc[i][1], 0, 0, 0);
;                 }
;                 __builtin_amdgcn_sched_barrier(0);
;             }
;             if (kt + 1 < nk) asm volatile("s_waitcnt vmcnt(0)" ::: "memory");
;             __builtin_amdgcn_s_barrier();
.LBB0_1429:
	s_mov_b32 s9, s13
	s_lshl_b32 s13, s9, 16
	s_xor_b32 s12, s13, 0x10000
	v_readfirstlane_b32 vcc_lo, v143
	s_nop 0
	s_add_u32 vcc_lo, vcc_lo, s12
	s_add_u32 s14, s4, 0xe380080
	s_addc_u32 s15, s5, 0
	s_mov_b32 m0, vcc_lo
	v_lshl_add_u64 v[164:165], v[136:137], 0, s[14:15]
	global_load_lds_dwordx4 v[164:165], off
	s_add_u32 s14, s4, 0xe3a0080
	s_addc_u32 s15, s5, 0
	s_add_u32 m0, vcc_lo, 0x2000
	v_lshl_add_u64 v[164:165], v[136:137], 0, s[14:15]
	global_load_lds_dwordx4 v[164:165], off
	s_add_u32 s14, s4, 0xe3c0080
	s_addc_u32 s15, s5, 0
	s_add_u32 m0, vcc_lo, 0x4000
	v_lshl_add_u64 v[164:165], v[136:137], 0, s[14:15]
	global_load_lds_dwordx4 v[164:165], off
	s_add_u32 s14, s4, 0xe3e0080
	s_addc_u32 s15, s5, 0
	s_add_u32 m0, vcc_lo, 0x6000
	v_lshl_add_u64 v[164:165], v[136:137], 0, s[14:15]
	global_load_lds_dwordx4 v[164:165], off
	s_add_u32 s14, s4, s20
	s_addc_u32 s15, s5, s21
	s_add_u32 m0, vcc_lo, 0x8000
	v_lshl_add_u64 v[164:165], v[138:139], 0, s[14:15]
	global_load_lds_dwordx4 v[164:165], off
	s_add_u32 s14, s4, 0x820080
	s_addc_u32 s15, s5, 0
	s_add_u32 m0, vcc_lo, 0xa000
	v_lshl_add_u64 v[164:165], v[138:139], 0, s[14:15]
	global_load_lds_dwordx4 v[164:165], off
	s_add_u32 s14, s4, s68
	s_addc_u32 s15, s5, s69
	s_add_u32 m0, vcc_lo, 0xc000
	v_lshl_add_u64 v[164:165], v[138:139], 0, s[14:15]
	global_load_lds_dwordx4 v[164:165], off
	s_add_u32 s14, s4, 0x860080
	s_addc_u32 s15, s5, 0
	s_add_u32 m0, vcc_lo, 0xe000
	v_lshl_add_u64 v[164:165], v[138:139], 0, s[14:15]
	global_load_lds_dwordx4 v[164:165], off
	v_add3_u32 v155, s13, v150, v149
	v_add_u32_e32 v155, v155, v152
	v_add3_u32 v0, s13, v147, v149
	v_add_u32_e32 v0, v0, v152
	ds_read_b128 v[208:211], v155 offset:32768
	ds_read_b128 v[212:215], v155 offset:36864
	s_waitcnt lgkmcnt(5)
	v_mfma_f32_32x32x16_bf16 v[114:129], v[192:195], v[156:159], v[114:129]
	v_mfma_f32_32x32x16_bf16 v[98:113], v[192:195], v[160:163], v[98:113]
	ds_read_b128 v[192:195], v0
	s_waitcnt lgkmcnt(5)
	v_mfma_f32_32x32x16_bf16 v[82:97], v[196:199], v[156:159], v[82:97]
	v_mfma_f32_32x32x16_bf16 v[66:81], v[196:199], v[160:163], v[66:81]
	ds_read_b128 v[196:199], v0 offset:4096
	s_waitcnt lgkmcnt(5)
	v_mfma_f32_32x32x16_bf16 v[50:65], v[200:203], v[156:159], v[50:65]
	v_mfma_f32_32x32x16_bf16 v[34:49], v[200:203], v[160:163], v[34:49]
	ds_read_b128 v[200:203], v0 offset:8192
	s_waitcnt lgkmcnt(5)
	v_mfma_f32_32x32x16_bf16 v[18:33], v[204:207], v[156:159], v[18:33]
	v_mfma_f32_32x32x16_bf16 v[2:17], v[204:207], v[160:163], v[2:17]
	ds_read_b128 v[204:207], v0 offset:12288
	v_add3_u32 v155, s13, v150, v149
	v_add_u32_e32 v155, v155, v153
	v_add3_u32 v0, s13, v147, v149
	v_add_u32_e32 v0, v0, v153
	ds_read_b128 v[156:159], v155 offset:32768
	ds_read_b128 v[160:163], v155 offset:36864
	s_waitcnt lgkmcnt(5)
	v_mfma_f32_32x32x16_bf16 v[114:129], v[192:195], v[208:211], v[114:129]
	v_mfma_f32_32x32x16_bf16 v[98:113], v[192:195], v[212:215], v[98:113]
	ds_read_b128 v[192:195], v0
	s_waitcnt lgkmcnt(5)
	v_mfma_f32_32x32x16_bf16 v[82:97], v[196:199], v[208:211], v[82:97]
	v_mfma_f32_32x32x16_bf16 v[66:81], v[196:199], v[212:215], v[66:81]
	ds_read_b128 v[196:199], v0 offset:4096
	s_waitcnt lgkmcnt(5)
	v_mfma_f32_32x32x16_bf16 v[50:65], v[200:203], v[208:211], v[50:65]
	v_mfma_f32_32x32x16_bf16 v[34:49], v[200:203], v[212:215], v[34:49]
	ds_read_b128 v[200:203], v0 offset:8192
	s_waitcnt lgkmcnt(5)
	v_mfma_f32_32x32x16_bf16 v[18:33], v[204:207], v[208:211], v[18:33]
	v_mfma_f32_32x32x16_bf16 v[2:17], v[204:207], v[212:215], v[2:17]
	ds_read_b128 v[204:207], v0 offset:12288
	v_add3_u32 v155, s13, v150, v149
	v_add_u32_e32 v155, v155, v154
	v_add3_u32 v0, s13, v147, v149
	v_add_u32_e32 v0, v0, v154
	ds_read_b128 v[208:211], v155 offset:32768
	ds_read_b128 v[212:215], v155 offset:36864
	s_waitcnt lgkmcnt(5)
	v_mfma_f32_32x32x16_bf16 v[114:129], v[192:195], v[156:159], v[114:129]
	v_mfma_f32_32x32x16_bf16 v[98:113], v[192:195], v[160:163], v[98:113]
	ds_read_b128 v[192:195], v0
	s_waitcnt lgkmcnt(5)
	v_mfma_f32_32x32x16_bf16 v[82:97], v[196:199], v[156:159], v[82:97]
	v_mfma_f32_32x32x16_bf16 v[66:81], v[196:199], v[160:163], v[66:81]
	ds_read_b128 v[196:199], v0 offset:4096
	s_waitcnt lgkmcnt(5)
	v_mfma_f32_32x32x16_bf16 v[50:65], v[200:203], v[156:159], v[50:65]
	v_mfma_f32_32x32x16_bf16 v[34:49], v[200:203], v[160:163], v[34:49]
	ds_read_b128 v[200:203], v0 offset:8192
	s_waitcnt lgkmcnt(5)
	v_mfma_f32_32x32x16_bf16 v[18:33], v[204:207], v[156:159], v[18:33]
	v_mfma_f32_32x32x16_bf16 v[2:17], v[204:207], v[160:163], v[2:17]
	ds_read_b128 v[204:207], v0 offset:12288
	s_waitcnt lgkmcnt(3)
	v_mfma_f32_32x32x16_bf16 v[114:129], v[192:195], v[208:211], v[114:129]
	v_mfma_f32_32x32x16_bf16 v[98:113], v[192:195], v[212:215], v[98:113]
	s_waitcnt lgkmcnt(2)
	v_mfma_f32_32x32x16_bf16 v[82:97], v[196:199], v[208:211], v[82:97]
	v_mfma_f32_32x32x16_bf16 v[66:81], v[196:199], v[212:215], v[66:81]
	s_waitcnt lgkmcnt(0)
	s_waitcnt vmcnt(0)
	s_barrier
; template <int EPI, int AMAP, int KOFFMODE, int K>
; __device__ __forceinline__ void gemm_phase(unsigned char* smem, const bf16_t* A, int lda, const bf16_t* Bt, int NT, const EpiArgs& ea) {
;     ...
;         for (int kt = 0; kt < nk; ++kt) {
;             if (kt + 1 < nk) GEMM_DMA(m0, n0, kt + 1, cur ^ 1);
;             else if (have_next) GEMM_DMA(m0n, n0n, 0, cur ^ 1);
;             const unsigned char* Ac = smem + cur * STGB + (wm * 128 + l31) * 128;
;             const unsigned char* Bc = smem + cur * STGB + 32768 + (wn * 64 + l31) * 128;
;             bf16x8 fa[2][4], fb[2][2];
;             fb[0][0] = *(const bf16x8*)(Bc + (((0) ^ yz) & 7) * 16);
;             fb[0][1] = *(const bf16x8*)(Bc + 32 * 128 + (((0) ^ yz) & 7) * 16);
; #pragma unroll
;             for (int i = 0; i < 4; ++i) fa[0][i] = *(const bf16x8*)(Ac + i * 32 * 128 + (((0) ^ yz) & 7) * 16);
; #pragma unroll
;             for (int s = 0; s < 4; ++s) {
;                 if (s < 3) {
;                     const int o_ = (((2 * (s + 1)) ^ yz) & 7) * 16;
;                     fb[(s + 1) & 1][0] = *(const bf16x8*)(Bc + o_);
;                     fb[(s + 1) & 1][1] = *(const bf16x8*)(Bc + 32 * 128 + o_);
; #pragma unroll
;                     for (int i = 0; i < 4; ++i) fa[(s + 1) & 1][i] = *(const bf16x8*)(Ac + i * 32 * 128 + o_);
;                 }
; #pragma unroll
;                 for (int i = 0; i < 4; ++i) {
;                     acc[i][0] = __builtin_amdgcn_mfma_f32_32x32x16_bf16(fa[s & 1][i], fb[s & 1][0], acc[i][0], 0, 0, 0);
;                     acc[i][1] = __builtin_amdgcn_mfma_f32_32x32x16_bf16(fa[s & 1][i], fb[s & 1][1], acc[i][1], 0, 0, 0);
;                 }
;                 __builtin_amdgcn_sched_barrier(0);
;             }
;             if (kt + 1 < nk) asm volatile("s_waitcnt vmcnt(0)" ::: "memory");
;             __builtin_amdgcn_s_barrier();
;             cur ^= 1;
;         }
	v_add3_u32 v155, s12, v150, v149
	v_add_u32_e32 v155, v155, v151
	v_add3_u32 v0, s12, v147, v149
	v_add_u32_e32 v0, v0, v151
	ds_read_b128 v[156:159], v155 offset:32768
	ds_read_b128 v[160:163], v155 offset:36864
	ds_read_b128 v[192:195], v0
	ds_read_b128 v[196:199], v0 offset:4096
	v_mfma_f32_32x32x16_bf16 v[50:65], v[200:203], v[208:211], v[50:65]
	v_mfma_f32_32x32x16_bf16 v[34:49], v[200:203], v[212:215], v[34:49]
	ds_read_b128 v[200:203], v0 offset:8192
	v_mfma_f32_32x32x16_bf16 v[18:33], v[204:207], v[208:211], v[18:33]
	v_mfma_f32_32x32x16_bf16 v[2:17], v[204:207], v[212:215], v[2:17]
	ds_read_b128 v[204:207], v0 offset:12288
	s_xor_b32 s13, s9, 1
	s_add_u32 s4, s4, 0x80
	s_addc_u32 s5, s5, 0
	s_cmpk_eq_i32 s4, 0x780
	s_cbranch_scc0 .LBB0_1429
	s_waitcnt lgkmcnt(0)
	s_andn2_b64 vcc, exec, s[2:3]
	s_lshl_b32 s2, s13, 16
	s_cbranch_vccnz .LBB0_1421
	v_add_u32_e32 v136, s8, v142
	s_xor_b32 s3, s2, 0x10000
	v_ashrrev_i32_e32 v137, 31, v136
	v_add_u32_e32 v138, s7, v142
	v_add_u32_e32 v0, s3, v143
	v_lshlrev_b64 v[136:137], 11, v[136:137]
	v_ashrrev_i32_e32 v139, 31, v138
	v_add_u32_e32 v155, 0x8000, v0
	v_readfirstlane_b32 s3, v0
	v_lshlrev_b64 v[138:139], 11, v[138:139]
	v_lshl_add_u64 v[136:137], v[130:131], 0, v[136:137]
	s_mov_b32 m0, s3
	v_readfirstlane_b32 s3, v155
	v_add_u32_e32 v155, 0x2000, v0
	v_lshl_add_u64 v[138:139], v[132:133], 0, v[138:139]
	global_load_lds_dwordx4 v[136:137], off
	s_mov_b32 m0, s3
	s_mov_b64 s[4:5], 0x20000
	v_readfirstlane_b32 s3, v155
	v_add_u32_e32 v155, 0xa000, v0
	global_load_lds_dwordx4 v[138:139], off
	v_lshl_add_u64 v[156:157], v[136:137], 0, s[4:5]
	s_mov_b32 m0, s3
	v_readfirstlane_b32 s3, v155
	v_add_u32_e32 v155, 0x4000, v0
	global_load_lds_dwordx4 v[156:157], off
	v_lshl_add_u64 v[156:157], v[138:139], 0, s[4:5]
	s_mov_b32 m0, s3
	s_mov_b64 s[4:5], 0x40000
	v_readfirstlane_b32 s3, v155
	v_add_u32_e32 v155, 0xc000, v0
	global_load_lds_dwordx4 v[156:157], off
	v_lshl_add_u64 v[156:157], v[136:137], 0, s[4:5]
	s_mov_b32 m0, s3
	v_readfirstlane_b32 s3, v155
	v_add_u32_e32 v155, 0x6000, v0
	global_load_lds_dwordx4 v[156:157], off
	v_lshl_add_u64 v[156:157], v[138:139], 0, s[4:5]
	s_mov_b32 m0, s3
	s_mov_b64 s[4:5], 0x60000
	v_readfirstlane_b32 s3, v155
	v_add_u32_e32 v0, 0xe000, v0
	global_load_lds_dwordx4 v[156:157], off
	v_lshl_add_u64 v[136:137], v[136:137], 0, s[4:5]
	s_mov_b32 m0, s3
	v_readfirstlane_b32 s3, v0
	global_load_lds_dwordx4 v[136:137], off
	v_lshl_add_u64 v[136:137], v[138:139], 0, s[4:5]
	s_mov_b32 m0, s3
	s_nop 0
	global_load_lds_dwordx4 v[136:137], off
	s_branch .LBB0_1421
